# plus static s_setprio 1 for NSA unit waves 4-7 (younger half)
# speedup vs baseline: 1.0081x; 1.0081x over previous
.LBB0_676:
	s_or_b64 exec, exec, s[0:1]
	v_readlane_b32 s0, v253, 5
	s_waitcnt lgkmcnt(0)
	s_barrier
	s_waitcnt vmcnt(7)
	v_mov_b32_e32 v1, s0
	ds_read_b32 v1, v1
	s_waitcnt lgkmcnt(0)
	s_barrier
	v_cmp_lt_i32_e64 s[0:1], s40, v1
	v_readfirstlane_b32 s3, v1
	s_and_b64 vcc, exec, s[0:1]
	s_cbranch_vccnz .LBB0_671
	v_writelane_b32 v254, s0, 21
	s_cmp_gt_i32 s3, 63
	s_nop 0
	v_writelane_b32 v254, s1, 22
	s_mov_b64 s[0:1], -1
	s_cbranch_scc0 .LBB0_854
	v_readfirstlane_b32 s98, v182
	s_nop 0
	s_cmp_lt_u32 s98, 0x100
	s_cbranch_scc1 .Lnsa_prio_skip
	s_setprio 1
.Lnsa_prio_skip:
	s_sub_i32 s0, s3, 64
	s_lshl_b32 s1, s3, 5
	s_and_b32 s1, s1, 0x1e0
	s_lshr_b32 s0, s0, 4
	s_sub_i32 s0, s1, s0
	s_add_i32 s0, s0, 31
	v_mov_b32_e32 v1, v182
	s_and_b32 s78, s0, 31
	v_and_b32_e32 v66, 31, v1
	s_waitcnt vmcnt(2)
	v_lshrrev_b32_e32 v15, 1, v1
	s_lshl_b32 s2, s78, 6
	v_and_or_b32 v68, v15, 32, v66
	s_lshr_b32 s88, s0, 5
	v_ashrrev_i32_e32 v71, 7, v1
	v_or_b32_e32 v67, s2, v68
	v_lshl_or_b32 v108, s88, 11, v67
	v_mov_b64_e32 v[2:3], s[58:59]
	s_movk_i32 s0, 0x1e00
	s_waitcnt vmcnt(0)
	v_lshlrev_b32_e32 v112, 6, v71
	v_bfe_u32 v69, v1, 5, 1
	v_mad_u64_u32 v[110:111], s[0:1], v108, s0, v[2:3]
	v_ashrrev_i32_e32 v113, 31, v112
	v_lshl_add_u64 v[2:3], v[112:113], 1, v[110:111]
	v_lshlrev_b32_e32 v4, 4, v69
	v_mov_b32_e32 v5, v0
	v_lshl_add_u64 v[2:3], v[2:3], 0, v[4:5]
	s_mov_b64 s[0:1], 0x1700
	v_mov_b32_e32 v109, v0
	v_lshl_add_u64 v[4:5], v[2:3], 0, s[0:1]
	v_add_co_u32_e32 v2, vcc, s86, v2
	s_addk_i32 s2, 0x220
	s_nop 0
	v_addc_co_u32_e32 v3, vcc, 0, v3, vcc
	global_load_dwordx4 v[80:83], v[4:5], off offset:32
	global_load_dwordx4 v[84:87], v[4:5], off offset:64
	global_load_dwordx4 v[88:91], v[2:3], off offset:1792
	global_load_dwordx4 v[92:95], v[4:5], off offset:96
	v_lshl_add_u32 v2, v71, 1, v71
	v_lshlrev_b64 v[4:5], 7, v[108:109]
	v_ashrrev_i32_e32 v3, 31, v2
	v_lshl_add_u64 v[4:5], s[60:61], 0, v[4:5]
	v_lshl_add_u64 v[2:3], v[2:3], 2, v[4:5]
	global_load_dwordx3 v[104:106], v[2:3], off offset:32
	s_and_b32 s6, s2, 0xe00
	v_writelane_b32 v254, s3, 23
	v_cmp_gt_i32_e32 vcc, s6, v1
	s_and_saveexec_b64 s[0:1], vcc
	s_cbranch_execz .LBB0_683
	s_lshl_b32 s2, s78, 2
	s_or_b32 s7, s2, 3
	s_lshl_b32 s2, s88, 15
	s_add_u32 s2, s66, s2
	v_and_b32_e32 v6, 15, v1
	s_addc_u32 s3, s67, 0
	s_lshl_b64 s[4:5], s[88:89], 15
	v_lshlrev_b32_e32 v2, 4, v6
	v_mov_b32_e32 v3, v0
	s_add_u32 s4, s66, s4
	v_lshl_add_u64 v[4:5], s[2:3], 0, v[2:3]
	s_mov_b64 s[2:3], 0x80000
	s_addc_u32 s5, s67, s5
	v_lshl_add_u64 v[10:11], v[4:5], 0, s[2:3]
	v_readlane_b32 s2, v253, 20
	v_lshl_add_u64 v[12:13], s[4:5], 0, v[2:3]
	v_lshl_add_u32 v14, v6, 3, 0
	v_mov_b32_e32 v2, s2
	s_movk_i32 s2, 0x420
	s_waitcnt vmcnt(6)
	v_mad_u32_u24 v16, v6, s2, v2
	s_mov_b64 s[2:3], 0
	v_mov_b32_e32 v17, v1
	s_branch .LBB0_681

.LBB0_853:
	v_mov_b32_e32 v2, v166
	s_nop 1
	v_permlane32_swap_b32_e32 v166, v2
	v_add_f32_e32 v2, v166, v2
	v_cmp_lt_f32_e32 vcc, 0, v2
	v_rcp_f32_e32 v2, v2
	v_readlane_b32 s56, v253, 32
	v_lshlrev_b64 v[4:5], 1, v[112:113]
	v_readlane_b32 s62, v253, 38
	v_readlane_b32 s63, v253, 39
	v_lshl_add_u64 v[6:7], v[110:111], 0, v[4:5]
	v_lshlrev_b32_e32 v20, 1, v150
	v_mov_b32_e32 v21, v0
	v_lshlrev_b64 v[8:9], 11, v[108:109]
	v_lshl_add_u64 v[6:7], v[6:7], 0, v[20:21]
	v_lshl_add_u64 v[8:9], s[62:63], 0, v[8:9]
	v_cndmask_b32_e32 v2, 0, v2, vcc
	v_lshl_add_u64 v[24:25], v[8:9], 0, v[4:5]
	v_add_co_u32_e32 v4, vcc, s86, v6
	s_mov_b64 s[0:1], 0x1c00
	s_nop 0
	v_addc_co_u32_e32 v5, vcc, 0, v7, vcc
	v_lshl_add_u64 v[22:23], v[6:7], 0, s[0:1]
	global_load_dwordx2 v[26:27], v[4:5], off offset:3072
	global_load_dwordx2 v[18:19], v[22:23], off offset:16
	global_load_dwordx2 v[16:17], v[22:23], off offset:32
	global_load_dwordx2 v[14:15], v[22:23], off offset:48
	global_load_dwordx2 v[12:13], v[22:23], off offset:64
	global_load_dwordx2 v[10:11], v[22:23], off offset:80
	global_load_dwordx2 v[8:9], v[22:23], off offset:96
	global_load_dwordx2 v[4:5], v[22:23], off offset:112
	v_mul_f32_e32 v1, 0xbfb8aa3b, v106
	v_exp_f32_e32 v1, v1
	v_lshl_add_u64 v[6:7], v[24:25], 0, v[20:21]
	v_readlane_b32 s92, v253, 51
	v_readlane_b32 s3, v254, 23
	v_add_f32_e32 v1, 1.0, v1
	v_rcp_f32_e32 v1, v1
	v_readlane_b32 s73, v253, 49
	v_readlane_b32 s58, v253, 34
	v_readlane_b32 s59, v253, 35
	v_mul_f32_e32 v2, v1, v2
	v_pk_fma_f32 v[20:21], v[64:65], v[2:3], v[144:145] op_sel_hi:[1,0,1]
	v_readlane_b32 s60, v253, 36
	v_readlane_b32 s61, v253, 37
	v_readlane_b32 s66, v253, 42
	v_readlane_b32 s67, v253, 43
	v_readlane_b32 s70, v253, 46
	v_readlane_b32 s71, v253, 47
	v_readlane_b32 s76, v253, 50
	v_readlane_b32 s93, v253, 52
	v_readlane_b32 s81, v253, 53
	v_readlane_b32 s84, v253, 54
	s_movk_i32 s97, 0x2000
	s_movk_i32 s38, 0x480
	s_movk_i32 s39, 0x7fff
	s_movk_i32 s40, 0x23f
	s_mov_b64 s[0:1], 0
	v_readlane_b32 s57, v253, 33
	v_readlane_b32 s64, v253, 40
	v_readlane_b32 s65, v253, 41
	v_readlane_b32 s68, v253, 44
	v_readlane_b32 s69, v253, 45
	s_waitcnt vmcnt(7)
	v_lshlrev_b32_e32 v22, 16, v26
	v_mul_f32_e32 v1, 0xbfb8aa3b, v22
	v_exp_f32_e32 v1, v1
	v_and_b32_e32 v23, 0xffff0000, v26
	v_add_f32_e32 v1, 1.0, v1
	v_rcp_f32_e32 v24, v1
	v_mul_f32_e32 v1, 0xbfb8aa3b, v23
	v_exp_f32_e32 v1, v1
	s_nop 0
	v_add_f32_e32 v1, 1.0, v1
	v_rcp_f32_e32 v25, v1
	s_nop 0
	v_pk_mul_f32 v[22:23], v[24:25], v[22:23]
	v_lshlrev_b32_e32 v24, 16, v27
	v_mul_f32_e32 v1, 0xbfb8aa3b, v24
	v_exp_f32_e32 v1, v1
	v_and_b32_e32 v25, 0xffff0000, v27
	v_pk_mul_f32 v[20:21], v[20:21], v[22:23]
	v_pk_fma_f32 v[22:23], v[66:67], v[2:3], v[142:143] op_sel_hi:[1,0,1]
	v_add_f32_e32 v1, 1.0, v1
	v_rcp_f32_e32 v26, v1
	v_mul_f32_e32 v1, 0xbfb8aa3b, v25
	v_exp_f32_e32 v1, v1
	v_cvt_pk_bf16_f32 v20, v20, v21
	v_add_f32_e32 v1, 1.0, v1
	v_rcp_f32_e32 v27, v1
	s_nop 0
	v_pk_mul_f32 v[24:25], v[26:27], v[24:25]
	s_nop 0
	v_pk_mul_f32 v[22:23], v[22:23], v[24:25]
	s_nop 0
	v_cvt_pk_bf16_f32 v21, v22, v23
	s_waitcnt vmcnt(6)
	v_lshlrev_b32_e32 v22, 16, v18
	v_mul_f32_e32 v1, 0xbfb8aa3b, v22
	v_exp_f32_e32 v1, v1
	v_and_b32_e32 v23, 0xffff0000, v18
	v_lshlrev_b32_e32 v18, 16, v19
	v_and_b32_e32 v19, 0xffff0000, v19
	v_add_f32_e32 v1, 1.0, v1
	v_rcp_f32_e32 v24, v1
	v_mul_f32_e32 v1, 0xbfb8aa3b, v23
	v_exp_f32_e32 v1, v1
	global_store_dwordx2 v[6:7], v[20:21], off offset:1536
	v_pk_fma_f32 v[20:21], v[68:69], v[2:3], v[140:141] op_sel_hi:[1,0,1]
	v_add_f32_e32 v1, 1.0, v1
	v_rcp_f32_e32 v25, v1
	v_mul_f32_e32 v1, 0xbfb8aa3b, v18
	v_exp_f32_e32 v1, v1
	v_pk_mul_f32 v[22:23], v[24:25], v[22:23]
	s_nop 0
	v_pk_mul_f32 v[20:21], v[20:21], v[22:23]
	v_add_f32_e32 v1, 1.0, v1
	v_rcp_f32_e32 v24, v1
	v_mul_f32_e32 v1, 0xbfb8aa3b, v19
	v_exp_f32_e32 v1, v1
	v_pk_fma_f32 v[22:23], v[70:71], v[2:3], v[138:139] op_sel_hi:[1,0,1]
	v_cvt_pk_bf16_f32 v20, v20, v21
	v_add_f32_e32 v1, 1.0, v1
	v_rcp_f32_e32 v25, v1
	s_nop 0
	v_pk_mul_f32 v[18:19], v[24:25], v[18:19]
	s_nop 0
	v_pk_mul_f32 v[18:19], v[22:23], v[18:19]
	s_nop 0
	v_cvt_pk_bf16_f32 v21, v18, v19
	global_store_dwordx2 v[6:7], v[20:21], off offset:1552
	s_waitcnt vmcnt(7)
	v_lshlrev_b32_e32 v20, 16, v16
	v_mul_f32_e32 v1, 0xbfb8aa3b, v20
	v_exp_f32_e32 v1, v1
	v_and_b32_e32 v21, 0xffff0000, v16
	v_lshlrev_b32_e32 v16, 16, v17
	v_and_b32_e32 v17, 0xffff0000, v17
	v_add_f32_e32 v1, 1.0, v1
	v_rcp_f32_e32 v22, v1
	v_mul_f32_e32 v1, 0xbfb8aa3b, v21
	v_exp_f32_e32 v1, v1
	v_pk_fma_f32 v[18:19], v[72:73], v[2:3], v[136:137] op_sel_hi:[1,0,1]
	v_add_f32_e32 v1, 1.0, v1
	v_rcp_f32_e32 v23, v1
	v_mul_f32_e32 v1, 0xbfb8aa3b, v16
	v_exp_f32_e32 v1, v1
	v_pk_mul_f32 v[20:21], v[22:23], v[20:21]
	s_nop 0
	v_pk_mul_f32 v[18:19], v[18:19], v[20:21]
	v_add_f32_e32 v1, 1.0, v1
	v_rcp_f32_e32 v22, v1
	v_mul_f32_e32 v1, 0xbfb8aa3b, v17
	v_exp_f32_e32 v1, v1
	v_pk_fma_f32 v[20:21], v[74:75], v[2:3], v[134:135] op_sel_hi:[1,0,1]
	v_cvt_pk_bf16_f32 v18, v18, v19
	v_add_f32_e32 v1, 1.0, v1
	v_rcp_f32_e32 v23, v1
	s_nop 0
	v_pk_mul_f32 v[16:17], v[22:23], v[16:17]
	s_nop 0
	v_pk_mul_f32 v[16:17], v[20:21], v[16:17]
	s_nop 0
	v_cvt_pk_bf16_f32 v19, v16, v17
	global_store_dwordx2 v[6:7], v[18:19], off offset:1568
	s_waitcnt vmcnt(7)
	v_lshlrev_b32_e32 v18, 16, v14
	v_mul_f32_e32 v1, 0xbfb8aa3b, v18
	v_exp_f32_e32 v1, v1
	v_and_b32_e32 v19, 0xffff0000, v14
	v_lshlrev_b32_e32 v14, 16, v15
	v_and_b32_e32 v15, 0xffff0000, v15
	v_add_f32_e32 v1, 1.0, v1
	v_rcp_f32_e32 v20, v1
	v_mul_f32_e32 v1, 0xbfb8aa3b, v19
	v_exp_f32_e32 v1, v1
	v_pk_fma_f32 v[16:17], v[76:77], v[2:3], v[132:133] op_sel_hi:[1,0,1]
	v_add_f32_e32 v1, 1.0, v1
	v_rcp_f32_e32 v21, v1
	v_mul_f32_e32 v1, 0xbfb8aa3b, v14
	v_exp_f32_e32 v1, v1
	v_pk_mul_f32 v[18:19], v[20:21], v[18:19]
	s_nop 0
	v_pk_mul_f32 v[16:17], v[16:17], v[18:19]
	v_add_f32_e32 v1, 1.0, v1
	v_rcp_f32_e32 v20, v1
	v_mul_f32_e32 v1, 0xbfb8aa3b, v15
	v_exp_f32_e32 v1, v1
	v_pk_fma_f32 v[18:19], v[78:79], v[2:3], v[130:131] op_sel_hi:[1,0,1]
	v_cvt_pk_bf16_f32 v16, v16, v17
	v_add_f32_e32 v1, 1.0, v1
	v_rcp_f32_e32 v21, v1
	s_nop 0
	v_pk_mul_f32 v[14:15], v[20:21], v[14:15]
	s_nop 0
	v_pk_mul_f32 v[14:15], v[18:19], v[14:15]
	s_nop 0
	v_cvt_pk_bf16_f32 v17, v14, v15
	global_store_dwordx2 v[6:7], v[16:17], off offset:1584
	s_waitcnt vmcnt(7)
	v_lshlrev_b32_e32 v16, 16, v12
	v_mul_f32_e32 v1, 0xbfb8aa3b, v16
	v_exp_f32_e32 v1, v1
	v_and_b32_e32 v17, 0xffff0000, v12
	v_lshlrev_b32_e32 v12, 16, v13
	v_and_b32_e32 v13, 0xffff0000, v13
	v_add_f32_e32 v1, 1.0, v1
	v_rcp_f32_e32 v18, v1
	v_mul_f32_e32 v1, 0xbfb8aa3b, v17
	v_exp_f32_e32 v1, v1
	v_pk_fma_f32 v[14:15], v[48:49], v[2:3], v[128:129] op_sel_hi:[1,0,1]
	v_add_f32_e32 v1, 1.0, v1
	v_rcp_f32_e32 v19, v1
	v_mul_f32_e32 v1, 0xbfb8aa3b, v12
	v_exp_f32_e32 v1, v1
	v_pk_mul_f32 v[16:17], v[18:19], v[16:17]
	s_nop 0
	v_pk_mul_f32 v[14:15], v[14:15], v[16:17]
	v_add_f32_e32 v1, 1.0, v1
	v_rcp_f32_e32 v18, v1
	v_mul_f32_e32 v1, 0xbfb8aa3b, v13
	v_exp_f32_e32 v1, v1
	v_pk_fma_f32 v[16:17], v[50:51], v[2:3], v[126:127] op_sel_hi:[1,0,1]
	v_cvt_pk_bf16_f32 v14, v14, v15
	v_add_f32_e32 v1, 1.0, v1
	v_rcp_f32_e32 v19, v1
	s_nop 0
	v_pk_mul_f32 v[12:13], v[18:19], v[12:13]
	s_nop 0
	v_pk_mul_f32 v[12:13], v[16:17], v[12:13]
	s_nop 0
	v_cvt_pk_bf16_f32 v15, v12, v13
	global_store_dwordx2 v[6:7], v[14:15], off offset:1600
	s_waitcnt vmcnt(7)
	v_lshlrev_b32_e32 v14, 16, v10
	v_mul_f32_e32 v1, 0xbfb8aa3b, v14
	v_exp_f32_e32 v1, v1
	v_and_b32_e32 v15, 0xffff0000, v10
	v_lshlrev_b32_e32 v10, 16, v11
	v_and_b32_e32 v11, 0xffff0000, v11
	v_add_f32_e32 v1, 1.0, v1
	v_rcp_f32_e32 v16, v1
	v_mul_f32_e32 v1, 0xbfb8aa3b, v15
	v_exp_f32_e32 v1, v1
	v_pk_fma_f32 v[12:13], v[52:53], v[2:3], v[124:125] op_sel_hi:[1,0,1]
	v_add_f32_e32 v1, 1.0, v1
	v_rcp_f32_e32 v17, v1
	v_mul_f32_e32 v1, 0xbfb8aa3b, v10
	v_exp_f32_e32 v1, v1
	v_pk_mul_f32 v[14:15], v[16:17], v[14:15]
	s_nop 0
	v_pk_mul_f32 v[12:13], v[12:13], v[14:15]
	v_add_f32_e32 v1, 1.0, v1
	v_rcp_f32_e32 v16, v1
	v_mul_f32_e32 v1, 0xbfb8aa3b, v11
	v_exp_f32_e32 v1, v1
	v_pk_fma_f32 v[14:15], v[54:55], v[2:3], v[122:123] op_sel_hi:[1,0,1]
	v_cvt_pk_bf16_f32 v12, v12, v13
	v_add_f32_e32 v1, 1.0, v1
	v_rcp_f32_e32 v17, v1
	s_nop 0
	v_pk_mul_f32 v[10:11], v[16:17], v[10:11]
	s_nop 0
	v_pk_mul_f32 v[10:11], v[14:15], v[10:11]
	s_nop 0
	v_cvt_pk_bf16_f32 v13, v10, v11
	global_store_dwordx2 v[6:7], v[12:13], off offset:1616
	s_waitcnt vmcnt(7)
	v_lshlrev_b32_e32 v12, 16, v8
	v_mul_f32_e32 v1, 0xbfb8aa3b, v12
	v_exp_f32_e32 v1, v1
	v_and_b32_e32 v13, 0xffff0000, v8
	v_lshlrev_b32_e32 v8, 16, v9
	v_and_b32_e32 v9, 0xffff0000, v9
	v_add_f32_e32 v1, 1.0, v1
	v_rcp_f32_e32 v14, v1
	v_mul_f32_e32 v1, 0xbfb8aa3b, v13
	v_exp_f32_e32 v1, v1
	v_pk_fma_f32 v[10:11], v[56:57], v[2:3], v[120:121] op_sel_hi:[1,0,1]
	v_add_f32_e32 v1, 1.0, v1
	v_rcp_f32_e32 v15, v1
	v_mul_f32_e32 v1, 0xbfb8aa3b, v8
	v_exp_f32_e32 v1, v1
	v_pk_mul_f32 v[12:13], v[14:15], v[12:13]
	s_nop 0
	v_pk_mul_f32 v[10:11], v[10:11], v[12:13]
	v_add_f32_e32 v1, 1.0, v1
	v_rcp_f32_e32 v14, v1
	v_mul_f32_e32 v1, 0xbfb8aa3b, v9
	v_exp_f32_e32 v1, v1
	v_pk_fma_f32 v[12:13], v[58:59], v[2:3], v[118:119] op_sel_hi:[1,0,1]
	v_cvt_pk_bf16_f32 v10, v10, v11
	v_add_f32_e32 v1, 1.0, v1
	v_rcp_f32_e32 v15, v1
	s_nop 0
	v_pk_mul_f32 v[8:9], v[14:15], v[8:9]
	s_nop 0
	v_pk_mul_f32 v[8:9], v[12:13], v[8:9]
	s_nop 0
	v_cvt_pk_bf16_f32 v11, v8, v9
	global_store_dwordx2 v[6:7], v[10:11], off offset:1632
	s_waitcnt vmcnt(7)
	v_lshlrev_b32_e32 v10, 16, v4
	v_mul_f32_e32 v1, 0xbfb8aa3b, v10
	v_exp_f32_e32 v1, v1
	v_and_b32_e32 v11, 0xffff0000, v4
	v_lshlrev_b32_e32 v4, 16, v5
	v_pk_fma_f32 v[8:9], v[60:61], v[2:3], v[116:117] op_sel_hi:[1,0,1]
	v_add_f32_e32 v1, 1.0, v1
	v_rcp_f32_e32 v12, v1
	v_mul_f32_e32 v1, 0xbfb8aa3b, v11
	v_exp_f32_e32 v1, v1
	v_and_b32_e32 v5, 0xffff0000, v5
	v_pk_fma_f32 v[2:3], v[62:63], v[2:3], v[114:115] op_sel_hi:[1,0,1]
	v_add_f32_e32 v1, 1.0, v1
	v_rcp_f32_e32 v13, v1
	v_mul_f32_e32 v1, 0xbfb8aa3b, v4
	v_exp_f32_e32 v1, v1
	v_pk_mul_f32 v[10:11], v[12:13], v[10:11]
	s_nop 0
	v_pk_mul_f32 v[8:9], v[8:9], v[10:11]
	v_add_f32_e32 v1, 1.0, v1
	v_rcp_f32_e32 v10, v1
	v_mul_f32_e32 v1, 0xbfb8aa3b, v5
	v_exp_f32_e32 v1, v1
	s_nop 0
	v_add_f32_e32 v1, 1.0, v1
	v_rcp_f32_e32 v11, v1
	s_nop 0
	v_pk_mul_f32 v[4:5], v[10:11], v[4:5]
	s_nop 0
	v_pk_mul_f32 v[2:3], v[2:3], v[4:5]
	v_cvt_pk_bf16_f32 v4, v8, v9
	v_cvt_pk_bf16_f32 v5, v2, v3
	global_store_dwordx2 v[6:7], v[4:5], off offset:1648
	s_barrier
	s_setprio 0
